# V^T stored token-blocked [t/256][d][256] (contiguous per GEMM tile; attention reader updated) instead of XOR swizzle; LRU pass-B loop-top vmcnt relaxed to 16
# speedup vs baseline: 1.0312x; 1.0036x over previous
; __device__ __forceinline__ float siluf_(float x) { return x * sigmoidf_(x); }
;     __device__ __forceinline__ void operator()(f32x4 (&acc)[2][2][4][2], const Unit& u, int wr, int wc, int fr, int fq, LAS unsigned char* lds) const {
;         const int seg = (u.pn * BM) / ldc >= 1 && O1 != nullptr ? 1 : 0;
;         const int colt = (O1 != nullptr) ? (u.pn * BM - seg * ldc) : u.pn * BM;
;         bf16_t* base = seg ? O1 : O0;
;         const bool act = seg && (act1 & 1);
;         const bool grp = !seg && (act1 & 2);
;         const int row0 = u.pm * BM + wr * 64 + fr, col0 = colt + wc * 32 + 8 * fq;
; #pragma unroll
;         for (int ai = 0; ai < 2; ++ai)
; #pragma unroll
;             for (int m = 0; m < 4; ++m) {
;                 bf16_t* rowp = base + (size_t)(row0 + ai * HALF + m * 16) * ldc + col0;
; #pragma unroll
;                 for (int bj = 0; bj < 2; ++bj) {
;                     f32x4 v0 = acc[ai][bj][m][0], v1 = acc[ai][bj][m][1];
;                     if (act) {
; #pragma unroll
;                         for (int j = 0; j < 4; ++j) { v0[j] = siluf_(v0[j]); v1[j] = siluf_(v1[j]); }
;                     }
;                     if (grp) { const int cc = col0 + bj * HALF; store8(base + ((size_t)(cc >> 4) * T + (row0 + ai * HALF + m * 16)) * 16 + (cc & 15), v0, v1); }
;                     else store8(rowp + bj * HALF, v0, v1);
;                 }
;             }
.LBB0_416:
	v_lshlrev_b32_e32 v160, 9, v148
	v_lshl_or_b32 v160, v150, 1, v160
	s_lshl_b32 s68, s83, 19
	s_lshl_b32 s69, s54, 17
	s_add_i32 s68, s68, s69
	v_mov_b32_e32 v162, s68
	v_mov_b32_e32 v163, 0
	v_lshl_add_u64 v[164:165], v[162:163], 0, s[26:27]
	v_mov_b32_e32 v167, 0
	v_mov_b32_e32 v169, 0
	v_lshl_add_u32 v146, s54, 8, v148
	v_lshl_or_b32 v144, s83, 8, v150
	v_ashrrev_i32_e32 v145, 31, v144
	v_ashrrev_i32_e32 v147, 31, v146
	v_lshl_add_u64 v[154:155], v[144:145], 1, s[26:27]
	v_lshlrev_b64 v[144:145], 16, v[146:147]
	v_lshl_add_u64 v[144:145], v[154:155], 0, v[144:145]
	v_cvt_pk_bf16_f32 v124, v124, v125
	v_cvt_pk_bf16_f32 v125, v126, v127
	v_cvt_pk_bf16_f32 v126, v120, v121
	v_cvt_pk_bf16_f32 v127, v122, v123
	v_mov_b32_e32 v166, v160
	v_lshl_add_u64 v[172:173], v[166:167], 0, v[164:165]
	global_store_dwordx4 v[172:173], v[124:127], off nt
	v_cvt_pk_bf16_f32 v112, v112, v113
	v_cvt_pk_bf16_f32 v113, v114, v115
	v_cvt_pk_bf16_f32 v114, v104, v105
	v_or_b32_e32 v104, 16, v146
	v_ashrrev_i32_e32 v105, 31, v104
	v_lshlrev_b64 v[104:105], 16, v[104:105]
	v_cvt_pk_bf16_f32 v115, v106, v107
	v_xor_b32_e32 v168, 0x100, v160
	v_lshl_add_u64 v[174:175], v[168:169], 0, v[164:165]
	global_store_dwordx4 v[174:175], v[112:115], off nt
	s_mov_b32 s4, 0x800000
	s_mov_b64 s[54:55], 0x800000
	v_lshl_add_u64 v[112:113], v[154:155], 0, v[104:105]
	v_cvt_pk_bf16_f32 v104, v116, v117
	v_cvt_pk_bf16_f32 v105, v118, v119
	v_cvt_pk_bf16_f32 v106, v108, v109
	v_cvt_pk_bf16_f32 v107, v110, v111
	v_xor_b32_e32 v166, 0x2000, v160
	v_lshl_add_u64 v[172:173], v[166:167], 0, v[164:165]
	global_store_dwordx4 v[172:173], v[104:107], off nt
	v_cvt_pk_bf16_f32 v96, v96, v97
	v_cvt_pk_bf16_f32 v97, v98, v99
	v_cvt_pk_bf16_f32 v98, v88, v89
	v_or_b32_e32 v88, 32, v146
	v_ashrrev_i32_e32 v89, 31, v88
	v_lshlrev_b64 v[88:89], 16, v[88:89]
	v_cvt_pk_bf16_f32 v99, v90, v91
	v_xor_b32_e32 v168, 0x2100, v160
	v_lshl_add_u64 v[174:175], v[168:169], 0, v[164:165]
	global_store_dwordx4 v[174:175], v[96:99], off nt
	s_nop 1
	v_lshl_add_u64 v[96:97], v[154:155], 0, v[88:89]
	v_cvt_pk_bf16_f32 v88, v100, v101
	v_cvt_pk_bf16_f32 v89, v102, v103
	v_cvt_pk_bf16_f32 v90, v92, v93
	v_cvt_pk_bf16_f32 v91, v94, v95
	v_xor_b32_e32 v166, 0x4000, v160
	v_lshl_add_u64 v[172:173], v[166:167], 0, v[164:165]
	global_store_dwordx4 v[172:173], v[88:91], off nt
	v_cvt_pk_bf16_f32 v80, v80, v81
	v_cvt_pk_bf16_f32 v81, v82, v83
	v_cvt_pk_bf16_f32 v82, v72, v73
	v_or_b32_e32 v72, 48, v146
	v_ashrrev_i32_e32 v73, 31, v72
	v_lshlrev_b64 v[72:73], 16, v[72:73]
	v_cvt_pk_bf16_f32 v83, v74, v75
	v_xor_b32_e32 v168, 0x4100, v160
	v_lshl_add_u64 v[174:175], v[168:169], 0, v[164:165]
	global_store_dwordx4 v[174:175], v[80:83], off nt
	s_nop 1
	v_lshl_add_u64 v[80:81], v[154:155], 0, v[72:73]
	v_cvt_pk_bf16_f32 v72, v84, v85
	v_cvt_pk_bf16_f32 v73, v86, v87
	v_cvt_pk_bf16_f32 v74, v76, v77
	v_cvt_pk_bf16_f32 v75, v78, v79
	v_xor_b32_e32 v166, 0x6000, v160
	v_lshl_add_u64 v[172:173], v[166:167], 0, v[164:165]
	global_store_dwordx4 v[172:173], v[72:75], off nt
	v_cvt_pk_bf16_f32 v68, v68, v69
	v_cvt_pk_bf16_f32 v69, v70, v71
	v_cvt_pk_bf16_f32 v70, v64, v65
	v_cvt_pk_bf16_f32 v71, v66, v67
	v_xor_b32_e32 v168, 0x6100, v160
	v_lshl_add_u64 v[174:175], v[168:169], 0, v[164:165]
	global_store_dwordx4 v[174:175], v[68:71], off nt
	v_cvt_pk_bf16_f32 v60, v60, v61
	v_cvt_pk_bf16_f32 v61, v62, v63
	v_cvt_pk_bf16_f32 v62, v56, v57
	v_add_co_u32_e32 v56, vcc, s4, v144
	v_lshl_add_u64 v[64:65], v[144:145], 0, s[54:55]
	s_nop 0
	v_addc_co_u32_e32 v57, vcc, 0, v145, vcc
	s_mov_b32 s4, 0x900000
	v_cvt_pk_bf16_f32 v63, v58, v59
	v_xor_b32_e32 v166, 0x10000, v160
	v_lshl_add_u64 v[172:173], v[166:167], 0, v[164:165]
	global_store_dwordx4 v[172:173], v[60:63], off nt
	v_cvt_pk_bf16_f32 v48, v48, v49
	v_cvt_pk_bf16_f32 v49, v50, v51
	v_cvt_pk_bf16_f32 v50, v40, v41
	v_cvt_pk_bf16_f32 v51, v42, v43
	v_xor_b32_e32 v168, 0x10100, v160
	v_lshl_add_u64 v[174:175], v[168:169], 0, v[164:165]
	global_store_dwordx4 v[174:175], v[48:51], off nt
	s_mov_b64 s[54:55], 0x900000
	v_cvt_pk_bf16_f32 v40, v52, v53
	v_cvt_pk_bf16_f32 v41, v54, v55
	v_cvt_pk_bf16_f32 v42, v44, v45
	v_add_co_u32_e32 v44, vcc, s4, v144
	v_lshl_add_u64 v[48:49], v[144:145], 0, s[54:55]
	s_nop 0
	v_addc_co_u32_e32 v45, vcc, 0, v145, vcc
	s_mov_b32 s4, 0xa00000
	v_cvt_pk_bf16_f32 v43, v46, v47
	v_xor_b32_e32 v166, 0x12000, v160
	v_lshl_add_u64 v[172:173], v[166:167], 0, v[164:165]
	global_store_dwordx4 v[172:173], v[40:43], off nt
	v_cvt_pk_bf16_f32 v32, v32, v33
	v_cvt_pk_bf16_f32 v33, v34, v35
	v_cvt_pk_bf16_f32 v34, v24, v25
	v_cvt_pk_bf16_f32 v35, v26, v27
	v_xor_b32_e32 v168, 0x12100, v160
	v_lshl_add_u64 v[174:175], v[168:169], 0, v[164:165]
	global_store_dwordx4 v[174:175], v[32:35], off nt
	s_mov_b64 s[54:55], 0xa00000
	v_cvt_pk_bf16_f32 v24, v36, v37
	v_cvt_pk_bf16_f32 v25, v38, v39
	v_cvt_pk_bf16_f32 v26, v28, v29
	v_add_co_u32_e32 v28, vcc, s4, v144
	v_lshl_add_u64 v[32:33], v[144:145], 0, s[54:55]
	s_nop 0
	v_addc_co_u32_e32 v29, vcc, 0, v145, vcc
	s_mov_b32 s4, 0xb00000
	v_cvt_pk_bf16_f32 v27, v30, v31
	v_xor_b32_e32 v166, 0x14000, v160
	v_lshl_add_u64 v[172:173], v[166:167], 0, v[164:165]
	global_store_dwordx4 v[172:173], v[24:27], off nt
	v_cvt_pk_bf16_f32 v16, v16, v17
	v_cvt_pk_bf16_f32 v17, v18, v19
	v_cvt_pk_bf16_f32 v18, v8, v9
	v_cvt_pk_bf16_f32 v19, v10, v11
	v_xor_b32_e32 v168, 0x14100, v160
	v_lshl_add_u64 v[174:175], v[168:169], 0, v[164:165]
	global_store_dwordx4 v[174:175], v[16:19], off nt
	v_cvt_pk_bf16_f32 v8, v20, v21
	v_cvt_pk_bf16_f32 v9, v22, v23
	v_cvt_pk_bf16_f32 v10, v12, v13
	v_add_co_u32_e32 v12, vcc, s4, v144
	s_mov_b64 s[54:55], 0xb00000
	s_nop 0
	v_addc_co_u32_e32 v13, vcc, 0, v145, vcc
	v_lshl_add_u64 v[16:17], v[144:145], 0, s[54:55]
	s_andn2_b64 vcc, exec, s[0:1]
	s_mov_b64 s[0:1], -1
	v_cvt_pk_bf16_f32 v11, v14, v15
	v_xor_b32_e32 v166, 0x16000, v160
	v_lshl_add_u64 v[172:173], v[166:167], 0, v[164:165]
	global_store_dwordx4 v[172:173], v[8:11], off nt
	v_cvt_pk_bf16_f32 v4, v4, v5
	v_cvt_pk_bf16_f32 v5, v6, v7
	v_cvt_pk_bf16_f32 v6, v0, v1
	v_cvt_pk_bf16_f32 v7, v2, v3
	v_xor_b32_e32 v168, 0x16100, v160
	v_lshl_add_u64 v[174:175], v[168:169], 0, v[164:165]
	global_store_dwordx4 v[174:175], v[4:7], off nt
	s_cbranch_vccnz .LBB0_405
	s_andn2_b64 vcc, exec, s[8:9]
	s_cbranch_vccnz .LBB0_404
	s_barrier
	s_branch .LBB0_404

; #define LAS __attribute__((address_space(3)))
; #define ATT_LOAD(kbi) do { const int k0_ = (kbi) * 64; _Pragma("unroll") for (int i_ = 0; i_ < 4; ++i_) { const int ci = (tid + 512 * i_) & 1023, hh_ = 2 * hp + (i_ >> 1); \
;         pk[i_] = *(const u32x4*)(Km + (rowbase + k0_ + (ci >> 4)) * 1024 + hh_ * 128 + (ci & 15) * 8); \
;         pv[i_] = *(const u32x4*)(VT + (size_t)(hh_ * 128 + (ci >> 3)) * T + rowbase + k0_ + (ci & 7) * 8); } } while (0)
; __device__ __forceinline__ void attn_unit(LAS unsigned char* lds, const bf16_t* Qm, const bf16_t* Km, const bf16_t* VT, const bf16_t* GBm, bf16_t* YB, int b, int hp, int qb) {
;     ...
;     const int tid = tidl_, wave = tid >> 6, lane = tid & 63, fr = lane & 15, fq = lane >> 4;
;     const int hsel = wave >> 2, h = 2 * hp + hsel;
;     const int q0 = qb * 64, qw = q0 + (hsel ? 3 - (wave & 3) : (wave & 3)) * 16;
;     const size_t rowbase = (size_t)b * SEQ;
;     LAS unsigned char* KL = lds + hsel * 35840;
;     LAS unsigned char* VL = KL + 17408;
;     volatile LAS int* FL = (volatile LAS int*)(lds + 71680);
;     bf16x8 qf[4];
;     { const bf16_t* qp = Qm + (rowbase + qw + fr) * 1024 + h * 128 + fq * 8;
; #pragma unroll
;       for (int ks = 0; ks < 4; ++ks) qf[ks] = *(const bf16x8*)(qp + ks * 32); }
;     f32x4 o[8];
; #pragma unroll
;     for (int d = 0; d < 8; ++d) o[d] = (f32x4){0.f, 0.f, 0.f, 0.f};
;     float Rs = 1.f;
;     int kb = q0 >> 6;
;     u32x4 pk[4], pv[4];
;     ...
;     ATT_LOAD(kb);
.LBB0_515:
	v_mov_b32_e32 v32, v226
	s_ashr_i32 s0, s39, 4
	s_sub_i32 s0, 0x7f, s0
	v_ashrrev_i32_e32 v33, 6, v32
	v_bitop3_b32 v0, v33, 3, v33 bitop3:0xc
	v_cmp_gt_u32_e32 vcc, s6, v32
	s_lshl_b32 s1, s39, 11
	s_lshl_b32 s56, s0, 6
	v_cndmask_b32_e32 v0, v0, v33, vcc
	s_and_b32 s60, s1, 0x6000
	s_lshl_b32 s1, s39, 8
	v_lshl_add_u32 v44, v0, 4, s56
	s_and_b32 s8, s1, 0x300
	s_and_b32 s61, s0, 0x3ffffff
	s_add_i32 s9, s56, s60
	s_lshl_b32 s0, s60, 1
	v_and_b32_e32 v34, 15, v32
	v_add_u32_e32 v0, s60, v44
	s_add_u32 s0, s26, s0
	v_bitop3_b32 v36, v32, s7, v104 bitop3:0x6c
	v_ashrrev_i32_e32 v35, 8, v32
	v_or_b32_e32 v80, v0, v34
	s_addc_u32 s1, s27, 0
	s_lshl_b64 s[4:5], s[56:57], 1
	v_lshrrev_b32_e32 v88, 4, v36
	v_lshlrev_b64 v[0:1], 11, v[80:81]
	v_lshl_add_u32 v84, v35, 7, s8
	s_add_u32 s4, s0, s4
	v_lshlrev_b32_e32 v22, 4, v32
	v_bfe_u32 v86, v32, 4, 6
	v_bfe_u32 v45, v32, 3, 7
	v_or_b32_e32 v26, s9, v88
	v_mov_b32_e32 v27, v81
	v_lshl_add_u64 v[0:1], s[46:47], 0, v[0:1]
	v_ashrrev_i32_e32 v85, 31, v84
	s_addc_u32 s5, s1, s5
	v_and_b32_e32 v16, 0x70, v22
	v_mov_b32_e32 v17, v81
	v_or_b32_e32 v20, s9, v86
	v_mov_b32_e32 v21, v81
	v_or_b32_e32 v46, s8, v45
	v_lshlrev_b64 v[26:27], 11, v[26:27]
	v_lshlrev_b64 v[82:83], 10, v[80:81]
	v_lshl_add_u64 v[0:1], v[84:85], 1, v[0:1]
	v_and_b32_e32 v80, 48, v32
	v_lshl_add_u64 v[18:19], s[4:5], 0, v[16:17]
	v_lshlrev_b64 v[20:21], 11, v[20:21]
	s_lshl_b32 s12, s8, 1
	s_mov_b32 s13, s57
	v_lshlrev_b32_e32 v24, 16, v46
	v_mov_b32_e32 v25, v81
	v_lshl_add_u64 v[26:27], s[44:45], 0, v[26:27]
	v_lshrrev_b32_e32 v47, 3, v36
	v_lshl_add_u64 v[12:13], v[0:1], 0, v[80:81]
	v_lshl_add_u64 v[20:21], s[44:45], 0, v[20:21]
	v_and_b32_e32 v22, 0xf0, v22
	v_mov_b32_e32 v23, v81
	v_lshl_add_u64 v[24:25], v[18:19], 0, v[24:25]
	v_lshl_add_u64 v[26:27], v[26:27], 0, s[12:13]
	v_or_b32_e32 v56, s8, v47
	v_lshl_add_u64 v[188:189], v[82:83], 0, v[84:85]
	v_bfe_u32 v190, v226, 4, 2
	v_lshl_or_b32 v188, v190, 2, v188
	v_lshlrev_b64 v[188:189], 1, v[188:189]
	v_lshl_add_u64 v[188:189], s[30:31], 0, v[188:189]
	global_load_dwordx2 v[172:173], v[188:189], off
	global_load_dwordx2 v[174:175], v[188:189], off offset:32
	global_load_dwordx2 v[176:177], v[188:189], off offset:64
	global_load_dwordx2 v[178:179], v[188:189], off offset:96
	global_load_dwordx2 v[180:181], v[188:189], off offset:128
	global_load_dwordx2 v[182:183], v[188:189], off offset:160
	global_load_dwordx2 v[184:185], v[188:189], off offset:192
	global_load_dwordx2 v[186:187], v[188:189], off offset:224
	global_load_dwordx4 v[0:3], v[12:13], off
	global_load_dwordx4 v[4:7], v[12:13], off offset:64
	global_load_dwordx4 v[8:11], v[12:13], off offset:128
	s_nop 0
	global_load_dwordx4 v[12:15], v[12:13], off offset:192
	v_lshl_add_u64 v[20:21], v[20:21], 0, s[12:13]
	v_lshl_add_u64 v[26:27], v[26:27], 0, v[22:23]
	v_lshrrev_b32_e32 v196, 3, v226
	v_and_b32_e32 v197, 7, v226
	v_lshlrev_b32_e32 v197, 4, v197
	v_add_u32_e32 v198, s8, v196
	v_lshlrev_b32_e32 v198, 9, v198
	v_or_b32_e32 v198, v198, v197
	v_mov_b32_e32 v199, 0
	s_mov_b32 s66, 0x8000
	s_mov_b32 s67, 0
	v_lshl_add_u64 v[216:217], v[198:199], 0, s[26:27]
	v_lshl_add_u64 v[218:219], v[216:217], 0, s[66:67]
	v_lshl_add_u64 v[220:221], v[218:219], 0, s[66:67]
	v_lshl_add_u64 v[222:223], v[220:221], 0, s[66:67]
	s_add_i32 s68, s60, s56
	s_lshr_b32 s66, s68, 8
	s_lshl_b32 s66, s66, 19
	s_bfe_u32 s67, s68, 0x20006
	s_lshl_b32 s67, s67, 7
	s_or_b32 s68, s66, s67
	s_mov_b32 s69, 0
	v_lshl_add_u64 v[200:201], v[216:217], 0, s[68:69]
	v_lshl_add_u64 v[202:203], v[218:219], 0, s[68:69]
	v_lshl_add_u64 v[204:205], v[220:221], 0, s[68:69]
	v_lshl_add_u64 v[206:207], v[222:223], 0, s[68:69]
	global_load_dwordx4 v[28:31], v[200:201], off
	global_load_dwordx4 v[40:43], v[26:27], off
	v_lshlrev_b32_e32 v24, 16, v56
	v_mov_b32_e32 v25, v81
	s_or_b32 s58, s8, 0x80
	v_lshl_add_u64 v[20:21], v[20:21], 0, v[22:23]
	v_lshl_add_u64 v[24:25], v[18:19], 0, v[24:25]
	v_or_b32_e32 v57, s58, v45
	global_load_dwordx4 v[36:39], v[20:21], off
	global_load_dwordx4 v[48:51], v[20:21], off offset:256
	v_lshlrev_b32_e32 v20, 16, v57
	v_mov_b32_e32 v21, v81
	global_load_dwordx4 v[52:55], v[202:203], off
	global_load_dwordx4 v[64:67], v[26:27], off offset:256
	v_or_b32_e32 v26, s58, v47
	v_lshl_add_u64 v[20:21], v[18:19], 0, v[20:21]
	v_lshlrev_b32_e32 v24, 16, v26
	v_mov_b32_e32 v25, v81
	v_lshl_add_u64 v[18:19], v[18:19], 0, v[24:25]
	global_load_dwordx4 v[68:71], v[204:205], off
	global_load_dwordx4 v[76:79], v[206:207], off
	v_lshl_add_u64 v[90:91], s[0:1], 0, v[16:17]
	v_lshlrev_b32_e32 v17, 1, v32
	v_and_b32_e32 v21, 3, v32
	v_and_or_b32 v17, v17, 24, v21
	v_add_u32_e32 v21, 16, v32
	v_mul_i32_i24_e32 v19, 0x8c00, v35
	v_and_b32_e32 v21, 63, v21
	v_add_u32_e32 v25, 48, v32
	v_mad_u32_u24 v35, v45, s38, 0
	v_mad_u32_u24 v45, v47, s38, 0
	s_add_u32 s12, s44, s12
	v_and_b32_e32 v25, 63, v25
	s_addc_u32 s13, s45, 0
	v_add_u32_e32 v113, v35, v16
	v_add_u32_e32 v115, v45, v16
	v_or_b32_e32 v16, v105, v21
	v_and_b32_e32 v107, 63, v32
	v_bfe_u32 v106, v32, 4, 2
	v_lshlrev_b32_e32 v18, 15, v46
	v_lshlrev_b32_e32 v20, 15, v56
	v_lshlrev_b32_e32 v24, 15, v57
	v_lshlrev_b32_e32 v26, 15, v26
	v_or_b32_e32 v109, 15, v44
	v_lshl_add_u32 v110, v33, 2, s28
	v_add3_u32 v19, 0, v19, v80
	v_or_b32_e32 v111, v44, v34
	v_mad_u32_u24 v27, v86, s29, 0
	v_mad_u32_u24 v44, v88, s29, 0
	v_lshl_add_u64 v[92:93], s[12:13], 0, v[22:23]
	v_lshl_add_u64 v[32:33], s[44:45], 0, v[22:23]
	v_mul_u32_u24_e32 v17, 0x110, v17
	v_mul_u32_u24_e32 v23, 0x90, v34
	s_lshl_b32 s12, s58, 1
	s_mov_b32 s13, s57
	v_mov_b32_e32 v60, v81
	v_mov_b32_e32 v61, v81
	v_mov_b32_e32 v62, v81
	v_mov_b32_e32 v63, v81
	v_lshlrev_b32_e32 v118, 2, v16
	v_or_b32_e32 v16, v105, v25
	v_lshl_add_u64 v[94:95], v[32:33], 0, s[12:13]
	v_add_u32_e32 v112, v27, v22
	v_add_u32_e32 v114, v44, v22
	v_lshlrev_b32_e32 v80, 1, v18
	v_lshlrev_b32_e32 v98, 1, v20
	v_lshlrev_b32_e32 v100, 1, v24
	v_lshlrev_b32_e32 v102, 1, v26
	v_add_u32_e32 v116, v19, v17
	v_add_u32_e32 v117, v19, v23
	v_lshlrev_b32_e32 v119, 2, v16
	v_mov_b64_e32 v[74:75], v[62:63]
	v_mov_b64_e32 v[56:57], v[60:61]
	v_mov_b64_e32 v[44:45], v[60:61]
	v_mov_b64_e32 v[32:33], v[60:61]
	v_mov_b64_e32 v[24:25], v[60:61]
	v_mov_b64_e32 v[20:21], v[60:61]
	v_mov_b64_e32 v[16:17], v[60:61]
	v_lshlrev_b32_e32 v108, 3, v106
	v_mov_b32_e32 v87, v81
	v_mov_b32_e32 v89, v81
	v_cmp_eq_u32_e64 s[0:1], 3, v106
	v_cmp_gt_u32_e64 s[10:11], 32, v107
	v_cmp_gt_u32_e64 s[4:5], 16, v107
	v_cmp_eq_u32_e64 s[8:9], 0, v107
	s_lshl_b32 s62, s61, 3
	s_sub_i32 s56, s56, 64
	v_mov_b32_e32 v96, 1.0
	s_mov_b32 s63, s57
	v_mov_b64_e32 v[72:73], v[60:61]
	v_mov_b64_e32 v[58:59], v[62:63]
	v_mov_b64_e32 v[46:47], v[62:63]
	v_mov_b64_e32 v[34:35], v[62:63]
	v_mov_b64_e32 v[26:27], v[62:63]
	v_mov_b64_e32 v[22:23], v[62:63]
	v_mov_b64_e32 v[18:19], v[62:63]
	s_branch .LBB0_517

; #define LAS __attribute__((address_space(3)))
; #define ATT_LOAD(kbi) do { const int k0_ = (kbi) * 64; _Pragma("unroll") for (int i_ = 0; i_ < 4; ++i_) { const int ci = (tid + 512 * i_) & 1023, hh_ = 2 * hp + (i_ >> 1); \
;         pk[i_] = *(const u32x4*)(Km + (rowbase + k0_ + (ci >> 4)) * 1024 + hh_ * 128 + (ci & 15) * 8); \
;         pv[i_] = *(const u32x4*)(VT + (size_t)(hh_ * 128 + (ci >> 3)) * T + rowbase + k0_ + (ci & 7) * 8); } } while (0)
; __device__ __forceinline__ void attn_unit(LAS unsigned char* lds, const bf16_t* Qm, const bf16_t* Km, const bf16_t* VT, const bf16_t* GBm, bf16_t* YB, int b, int hp, int qb) {
;     ...
; #pragma unroll
;         for (int i = 0; i < 4; ++i) { const int ci = (tid + 512 * i) & 1023; LAS unsigned char* kd = lds + (i >> 1) * 35840;
;             *(LAS u32x4*)(kd + (ci >> 4) * 272 + (ci & 15) * 16) = pk[i];
;             *(LAS u32x4*)(kd + 17408 + (ci >> 3) * 144 + (ci & 7) * 16) = pv[i]; }
;         __syncthreads();
;         if (kb > 0) ATT_LOAD(kb - 1);
.LBB0_517:
	s_cmp_lt_i32 s61, 1
	s_waitcnt vmcnt(5)
	ds_write_b128 v112, v[36:39]
	ds_write_b128 v113, v[28:31] offset:17408
	ds_write_b128 v114, v[40:43]
	s_waitcnt vmcnt(3)
	ds_write_b128 v115, v[52:55] offset:17408
	ds_write_b128 v112, v[48:51] offset:35840
	s_waitcnt vmcnt(1)
	ds_write_b128 v113, v[68:71] offset:53248
	ds_write_b128 v114, v[64:67] offset:35840
	s_waitcnt vmcnt(0)
	ds_write_b128 v115, v[76:79] offset:53248
	s_waitcnt lgkmcnt(0)
	s_barrier
	s_cbranch_scc1 .LBB0_519
	s_add_i32 s12, s56, s60
	v_or_b32_e32 v28, s12, v86
	v_mov_b32_e32 v29, v87
	v_or_b32_e32 v40, s12, v88
	v_mov_b32_e32 v41, v89
	v_lshl_add_u64 v[64:65], s[56:57], 1, v[90:91]
	v_lshlrev_b64 v[48:49], 11, v[28:29]
	v_lshlrev_b64 v[66:67], 11, v[40:41]
	v_mov_b32_e32 v99, v81
	v_mov_b32_e32 v101, v81
	v_mov_b32_e32 v103, v81
	v_lshl_add_u64 v[28:29], v[92:93], 0, v[48:49]
	v_lshl_add_u64 v[30:31], v[64:65], 0, v[80:81]
	v_lshl_add_u64 v[40:41], v[92:93], 0, v[66:67]
	v_lshl_add_u64 v[50:51], v[64:65], 0, v[98:99]
	v_lshl_add_u64 v[48:49], v[94:95], 0, v[48:49]
	v_lshl_add_u64 v[68:69], v[64:65], 0, v[100:101]
	v_lshl_add_u64 v[66:67], v[94:95], 0, v[66:67]
	v_lshl_add_u64 v[76:77], v[64:65], 0, v[102:103]
	s_mov_b32 s68, s12
	s_lshr_b32 s66, s68, 8
	s_lshl_b32 s66, s66, 19
	s_bfe_u32 s67, s68, 0x20006
	s_lshl_b32 s67, s67, 7
	s_or_b32 s68, s66, s67
	s_mov_b32 s69, 0
	v_lshl_add_u64 v[200:201], v[216:217], 0, s[68:69]
	v_lshl_add_u64 v[202:203], v[218:219], 0, s[68:69]
	v_lshl_add_u64 v[204:205], v[220:221], 0, s[68:69]
	v_lshl_add_u64 v[206:207], v[222:223], 0, s[68:69]
	global_load_dwordx4 v[36:39], v[28:29], off
	s_nop 0
	global_load_dwordx4 v[28:31], v[200:201], off
	s_nop 0
	global_load_dwordx4 v[40:43], v[40:41], off
	s_nop 0
	global_load_dwordx4 v[52:55], v[202:203], off
	s_nop 0
	global_load_dwordx4 v[48:51], v[48:49], off
	s_nop 0
	global_load_dwordx4 v[68:71], v[204:205], off
	s_nop 0
	global_load_dwordx4 v[64:67], v[66:67], off
	s_nop 0
	global_load_dwordx4 v[76:79], v[206:207], off

; #define LRU_LOADX(st_) do { const int t0_ = chunk * LRU_LC + (st_) * 64; _Pragma("unroll") for (int i_ = 0; i_ < 2; ++i_) _Pragma("unroll") for (int k_ = 0; k_ < 4; ++k_) { \
;         const int ts_ = t0_ + tok + 32 * i_ - 3 + k_; xw[i_][k_] = (ts_ >= 0) ? *(const u32x4*)(xbase + (size_t)ts_ * 1024) : (u32x4){0u, 0u, 0u, 0u}; } } while (0)
; template <bool PASSB>
; __device__ __forceinline__ void lru_unit(LAS unsigned char* lds, const Params& p, int b, int hd, int chunk) {
;     ...
;     const float brv = p.in[9][gch], biv = p.in[11][gch];
;     float clv; { const float L = p.in[12][gch]; clv = -8.0f * (fmaxf(-L, 0.f) + log1pf(expf(-fabsf(L)))); }
;     const int ch8 = (tid & 15) * 8, tok = tid >> 4;
;     float Cst = 0.f, Pacc = 1.f;
;     if (PASSB) {
;         f32x2 e[LRU_NC];
; #pragma unroll
;         for (int j = 0; j < LRU_NC - 1; ++j) { const int jj = j < chunk ? j : 0; e[j] = *(const f32x2*)(AGG + ((size_t)(b * LRU_NC + jj) * 1024 + gch) * 2); }
; #pragma unroll
;         for (int j = 0; j < LRU_NC - 1; ++j) if (j < chunk) Cst = e[j][0] * Cst + e[j][1];
;     }
;     f32x4 cw0[4], cw1[4];
; #pragma unroll
;     for (int k = 0; k < 4; ++k) { cw0[k] = *(const f32x4*)(p.in[6] + k * 1024 + hd * 128 + ch8); cw1[k] = *(const f32x4*)(p.in[6] + k * 1024 + hd * 128 + ch8 + 4); }
;     const f32x4 cb0 = *(const f32x4*)(p.in[7] + hd * 128 + ch8), cb1 = *(const f32x4*)(p.in[7] + hd * 128 + ch8 + 4);
;     u32x4 xw[2][4];
;     const bf16_t* xbase = XA + ((size_t)b * SEQ) * 1024 + hd * 128 + ch8;
;     ...
;     LRU_LOADX(0);
.LBB0_598:
	s_or_b64 exec, exec, s[60:61]
	s_waitcnt vmcnt(15)
	v_fmac_f32_e32 v125, v124, v129
	v_cndmask_b32_e64 v112, v129, v125, s[0:1]
	s_waitcnt vmcnt(14)
	v_fmac_f32_e32 v109, v108, v112
	v_cndmask_b32_e64 v108, v112, v109, s[14:15]
	s_waitcnt vmcnt(13)
	v_fmac_f32_e32 v107, v106, v108
	v_cndmask_b32_e64 v106, v108, v107, s[4:5]
	s_waitcnt vmcnt(12)
	v_fmac_f32_e32 v105, v104, v106
	v_cndmask_b32_e64 v104, v106, v105, s[8:9]
	v_mul_f32_e64 v105, |v117|, s62
	v_rndne_f32_e32 v106, v105
	v_sub_f32_e32 v107, v105, v106
	v_fma_f32 v105, |v117|, s62, -v105
	s_mov_b32 s0, 0xb2a5705f
	v_fma_f32 v105, |v117|, s0, v105
	v_add_f32_e32 v105, v107, v105
	s_waitcnt vmcnt(11)
	v_fmac_f32_e32 v127, v126, v104
	v_exp_f32_e32 v105, v105
	v_cvt_i32_f32_e32 v106, v106
	v_cndmask_b32_e64 v104, v104, v127, s[12:13]
	s_waitcnt vmcnt(10)
	v_fmac_f32_e32 v111, v110, v104
	v_cndmask_b32_e64 v137, v104, v111, s[10:11]
	v_max_f32_e64 v104, -v117, -v117
	s_mov_b32 s0, 0x42ce8ed0
	v_max_f32_e32 v107, 0, v104
	v_ldexp_f32 v104, v105, v106
	v_cmp_ngt_f32_e64 vcc, |v117|, s0
	s_mov_b32 s0, 0xc2b17218
	s_lshl_b64 s[4:5], s[58:59], 13
	v_cndmask_b32_e32 v104, 0, v104, vcc
	v_cmp_nlt_f32_e64 vcc, |v117|, s0
	s_mov_b32 s0, 0x3f2aaaab
	s_ashr_i32 s9, s83, 31
	v_cndmask_b32_e32 v106, v134, v104, vcc
	v_add_f32_e32 v108, 1.0, v106
	v_add_f32_e32 v104, -1.0, v108
	v_sub_f32_e32 v105, v104, v108
	v_add_f32_e32 v105, 1.0, v105
	v_sub_f32_e32 v104, v106, v104
	v_add_f32_e32 v109, v104, v105
	v_frexp_mant_f32_e32 v110, v108
	v_cvt_f64_f32_e32 v[104:105], v108
	v_frexp_exp_i32_f64_e32 v104, v[104:105]
	v_cmp_gt_f32_e32 vcc, s0, v110
	s_mov_b32 s0, 0x3f317218
	s_add_u32 s8, s83, s4
	v_subbrev_co_u32_e32 v104, vcc, 0, v104, vcc
	v_sub_u32_e32 v105, 0, v104
	v_ldexp_f32 v108, v108, v105
	v_ldexp_f32 v105, v109, v105
	v_add_f32_e32 v109, -1.0, v108
	v_add_f32_e32 v112, 1.0, v108
	v_add_f32_e32 v110, 1.0, v109
	v_add_f32_e32 v117, -1.0, v112
	v_sub_f32_e32 v110, v108, v110
	v_sub_f32_e32 v108, v108, v117
	v_add_f32_e32 v110, v105, v110
	v_add_f32_e32 v105, v105, v108
	v_add_f32_e32 v108, v112, v105
	v_rcp_f32_e32 v117, v108
	v_add_f32_e32 v111, v109, v110
	v_sub_f32_e32 v109, v109, v111
	v_add_f32_e32 v109, v110, v109
	v_sub_f32_e32 v110, v112, v108
	v_add_f32_e32 v105, v105, v110
	v_mul_f32_e32 v110, v111, v117
	v_mul_f32_e32 v112, v108, v110
	v_fma_f32 v119, v110, v108, -v112
	v_fmac_f32_e32 v119, v110, v105
	v_add_f32_e32 v121, v112, v119
	v_sub_f32_e32 v124, v111, v121
	v_sub_f32_e32 v111, v111, v124
	v_sub_f32_e32 v112, v121, v112
	v_sub_f32_e32 v111, v111, v121
	v_add_f32_e32 v109, v109, v111
	v_sub_f32_e32 v111, v112, v119
	v_add_f32_e32 v109, v111, v109
	v_add_f32_e32 v111, v124, v109
	v_mul_f32_e32 v112, v117, v111
	v_mul_f32_e32 v119, v108, v112
	v_fma_f32 v108, v112, v108, -v119
	v_fmac_f32_e32 v108, v112, v105
	v_sub_f32_e32 v105, v124, v111
	v_add_f32_e32 v105, v109, v105
	v_add_f32_e32 v109, v119, v108
	v_sub_f32_e32 v121, v111, v109
	v_sub_f32_e32 v111, v111, v121
	v_sub_f32_e32 v119, v109, v119
	v_sub_f32_e32 v109, v111, v109
	v_add_f32_e32 v105, v105, v109
	v_sub_f32_e32 v108, v119, v108
	v_cvt_f32_i32_e32 v104, v104
	v_add_f32_e32 v105, v108, v105
	v_add_f32_e32 v108, v110, v112
	v_add_f32_e32 v105, v121, v105
	v_sub_f32_e32 v109, v108, v110
	v_mul_f32_e32 v105, v117, v105
	v_sub_f32_e32 v109, v112, v109
	v_add_f32_e32 v105, v109, v105
	v_mul_f32_e32 v112, 0x3f317218, v104
	v_add_f32_e32 v109, v108, v105
	v_fma_f32 v117, v104, s0, -v112
	v_mul_f32_e32 v110, v109, v109
	v_fmac_f32_e32 v117, 0xb102e308, v104
	v_sub_f32_e32 v104, v109, v108
	v_fmamk_f32 v111, v110, 0x3e9b6dac, v132
	v_sub_f32_e32 v104, v105, v104
	v_add_f32_e32 v105, v112, v117
	v_fmaak_f32 v111, v110, v111, 0x3f2aaada
	v_sub_f32_e32 v108, v105, v112
	v_ldexp_f32 v112, v109, 1
	v_mul_f32_e32 v109, v109, v110
	v_mul_f32_e32 v109, v109, v111
	v_add_f32_e32 v110, v112, v109
	v_sub_f32_e32 v111, v110, v112
	v_ldexp_f32 v104, v104, 1
	v_sub_f32_e32 v109, v109, v111
	v_add_f32_e32 v104, v104, v109
	v_add_f32_e32 v109, v110, v104
	v_sub_f32_e32 v110, v109, v110
	v_sub_f32_e32 v104, v104, v110
	v_add_f32_e32 v110, v105, v109
	v_sub_f32_e32 v111, v110, v105
	v_sub_f32_e32 v112, v110, v111
	v_sub_f32_e32 v108, v117, v108
	v_sub_f32_e32 v105, v105, v112
	v_sub_f32_e32 v109, v109, v111
	v_add_f32_e32 v105, v109, v105
	v_add_f32_e32 v109, v108, v104
	v_sub_f32_e32 v111, v109, v108
	v_sub_f32_e32 v112, v109, v111
	v_sub_f32_e32 v108, v108, v112
	v_sub_f32_e32 v104, v104, v111
	v_add_f32_e32 v105, v109, v105
	v_add_f32_e32 v104, v104, v108
	v_add_f32_e32 v108, v110, v105
	v_sub_f32_e32 v109, v108, v110
	v_sub_f32_e32 v105, v105, v109
	v_add_f32_e32 v104, v104, v105
	s_mov_b32 s0, 0x7f800000
	v_add_f32_e32 v104, v108, v104
	v_cmp_neq_f32_e32 vcc, s0, v106
	v_ashrrev_i32_e32 v105, 6, v138
	v_and_b32_e32 v105, 0xffffffc, v105
	v_cndmask_b32_e32 v104, v134, v104, vcc
	v_cmp_lt_f32_e64 vcc, |v106|, s63
	v_mov_b32_e32 v117, v113
	s_addc_u32 s9, s9, s5
	v_cndmask_b32_e32 v104, v104, v106, vcc
	v_add_f32_e32 v104, v107, v104
	v_mul_f32_e32 v119, 0xc1000000, v104
	v_lshrrev_b32_e32 v104, 2, v138
	v_and_or_b32 v104, v104, 48, v135
	v_add_u32_e32 v105, v104, v105
	v_mul_lo_u32 v139, v105, s64
	v_add_u32_e32 v105, 32, v128
	v_lshrrev_b32_e32 v105, 2, v105
	v_and_b32_e32 v105, 0xffffffc, v105
	v_add_u32_e32 v104, v105, v104
	v_mul_lo_u32 v131, v104, s64
	v_lshl_add_u64 v[104:105], s[8:9], 0, v[116:117]
	v_lshlrev_b64 v[104:105], 10, v[104:105]
	v_add_u32_e32 v106, v141, v140
	v_or_b32_e32 v104, s56, v104
	v_ashrrev_i32_e32 v107, 31, v106
	v_lshl_add_u64 v[104:105], v[104:105], 0, v[106:107]
	v_lshl_add_u64 v[124:125], v[104:105], 1, s[78:79]
	v_lshl_add_u32 v104, s82, 10, v128
	s_lshl_b32 s8, s28, 13
	v_subrev_u32_e32 v104, s8, v104
	v_add_u32_e32 v126, 0x60, v104
	v_and_or_b32 v104, v133, 64, v140
	s_mov_b32 s14, 0
	v_cmp_eq_u32_e64 s[0:1], 2, v135
	v_mul_lo_u32 v138, v128, s65
	v_mul_u32_u24_e32 v130, 0x110, v140
	v_mul_u32_u24_e32 v121, 0x2100, v135
	s_mov_b64 s[8:9], 0
	v_lshlrev_b32_e32 v117, 2, v104
	s_waitcnt vmcnt(0)
; #define LAS __attribute__((address_space(3)))
; __device__ __forceinline__ unsigned cvt_pk_bf16(float lo, float hi) { unsigned r; asm volatile("v_cvt_pk_bf16_f32 %0, %1, %2" : "=v"(r) : "v"(lo), "v"(hi)); return r; }
; __device__ __forceinline__ float bflo(unsigned w) { return __uint_as_float(w << 16); }
; __device__ __forceinline__ float bfhi(unsigned w) { return __uint_as_float(w & 0xffff0000u); }
; #define LRU_LOADX(st_) do { const int t0_ = chunk * LRU_LC + (st_) * 64; _Pragma("unroll") for (int i_ = 0; i_ < 2; ++i_) _Pragma("unroll") for (int k_ = 0; k_ < 4; ++k_) { \
;         const int ts_ = t0_ + tok + 32 * i_ - 3 + k_; xw[i_][k_] = (ts_ >= 0) ? *(const u32x4*)(xbase + (size_t)ts_ * 1024) : (u32x4){0u, 0u, 0u, 0u}; } } while (0)
; template <bool PASSB>
; __device__ __forceinline__ void lru_unit(LAS unsigned char* lds, const Params& p, int b, int hd, int chunk) {
;     ...
;     for (int st = 0; st < NST; ++st) {
;         const int t0 = chunk * LRU_LC + st * 64;
;         LAS unsigned char* XCB = lds + (st & 1) * 51200;
;         LAS float* XCF = (LAS float*)(XCB + 17408);
; #pragma unroll
;         for (int i = 0; i < 2; ++i) {
;             const int token = tok + 32 * i;
;             f32x4 a0 = cb0, a1 = cb1;
; #pragma unroll
;             for (int k = 0; k < 4; ++k) {
;                 const u32x4 x4 = xw[i][k];
;                 a0[0] += cw0[k][0] * bflo(x4.x); a0[1] += cw0[k][1] * bfhi(x4.x); a0[2] += cw0[k][2] * bflo(x4.y); a0[3] += cw0[k][3] * bfhi(x4.y);
;                 a1[0] += cw1[k][0] * bflo(x4.z); a1[1] += cw1[k][1] * bfhi(x4.z); a1[2] += cw1[k][2] * bflo(x4.w); a1[3] += cw1[k][3] * bfhi(x4.w);
;             }
;             u32x4 w; w.x = cvt_pk_bf16(a0[0], a0[1]); w.y = cvt_pk_bf16(a0[2], a0[3]); w.z = cvt_pk_bf16(a1[0], a1[1]); w.w = cvt_pk_bf16(a1[2], a1[3]);
;             *(LAS u32x4*)(XCB + (((token >> 2) & 3) * 16 + (token >> 4) * 4 + (token & 3)) * 272 + ch8 * 2) = w;
;             *(LAS f32x4*)(XCF + token * 132 + ch8) = a0; *(LAS f32x4*)(XCF + token * 132 + ch8 + 4) = a1;
;         }
;         __syncthreads();
;         if (st + 1 < NST) LRU_LOADX(st + 1);
.LBB0_599:
	s_waitcnt vmcnt(16)
	v_lshlrev_b32_e32 v104, 16, v72
	v_and_b32_e32 v105, 0xffff0000, v72
	v_lshlrev_b32_e32 v72, 16, v73
	v_and_b32_e32 v73, 0xffff0000, v73
	v_pk_fma_f32 v[104:105], v[52:53], v[104:105], v[68:69]
	v_lshlrev_b32_e32 v106, 16, v80
	v_and_b32_e32 v107, 0xffff0000, v80
	v_pk_fma_f32 v[72:73], v[54:55], v[72:73], v[70:71]
	v_lshlrev_b32_e32 v80, 16, v81
	v_and_b32_e32 v81, 0xffff0000, v81
	v_pk_fma_f32 v[104:105], v[56:57], v[106:107], v[104:105]
	v_lshlrev_b32_e32 v106, 16, v84
	v_and_b32_e32 v107, 0xffff0000, v84
	v_pk_fma_f32 v[72:73], v[58:59], v[80:81], v[72:73]
	v_lshlrev_b32_e32 v80, 16, v85
	v_and_b32_e32 v81, 0xffff0000, v85
	v_pk_fma_f32 v[104:105], v[60:61], v[106:107], v[104:105]
	v_lshlrev_b32_e32 v106, 16, v96
	v_and_b32_e32 v107, 0xffff0000, v96
	v_pk_fma_f32 v[72:73], v[62:63], v[80:81], v[72:73]
	v_lshlrev_b32_e32 v80, 16, v97
	v_and_b32_e32 v81, 0xffff0000, v97
	v_pk_fma_f32 v[104:105], v[64:65], v[106:107], v[104:105]
	v_pk_fma_f32 v[106:107], v[66:67], v[80:81], v[72:73]
	v_lshlrev_b32_e32 v72, 16, v74
	v_and_b32_e32 v73, 0xffff0000, v74
	v_pk_fma_f32 v[72:73], v[32:33], v[72:73], v[48:49]
	v_lshlrev_b32_e32 v80, 16, v82
	v_and_b32_e32 v81, 0xffff0000, v82
	s_bitcmp1_b32 s14, 0
	v_pk_fma_f32 v[72:73], v[36:37], v[80:81], v[72:73]
	v_lshlrev_b32_e32 v80, 16, v86
	v_and_b32_e32 v81, 0xffff0000, v86
	s_cselect_b32 s10, 0xc800, 0
	v_pk_fma_f32 v[72:73], v[40:41], v[80:81], v[72:73]
	v_lshlrev_b32_e32 v80, 16, v98
	v_and_b32_e32 v81, 0xffff0000, v98
	v_lshlrev_b32_e32 v74, 16, v75
	v_and_b32_e32 v75, 0xffff0000, v75
	s_add_i32 s12, s10, 0
	v_pk_fma_f32 v[72:73], v[44:45], v[80:81], v[72:73]
	v_pk_fma_f32 v[74:75], v[34:35], v[74:75], v[50:51]
	v_lshlrev_b32_e32 v80, 16, v83
	v_and_b32_e32 v81, 0xffff0000, v83
	v_add_u32_e32 v108, s12, v120
	v_pk_fma_f32 v[74:75], v[38:39], v[80:81], v[74:75]
	v_lshlrev_b32_e32 v80, 16, v87
	v_and_b32_e32 v81, 0xffff0000, v87
	v_pk_fma_f32 v[74:75], v[42:43], v[80:81], v[74:75]
	v_lshlrev_b32_e32 v80, 16, v99
	v_and_b32_e32 v81, 0xffff0000, v99
	v_add_u32_e32 v84, v108, v139
	v_pk_fma_f32 v[74:75], v[46:47], v[80:81], v[74:75]
	v_cvt_pk_bf16_f32 v80, v104, v105
	v_cvt_pk_bf16_f32 v81, v106, v107
	v_cvt_pk_bf16_f32 v82, v72, v73
	v_add_u32_e32 v85, v108, v131
	v_cvt_pk_bf16_f32 v83, v74, v75
	ds_write_b128 v84, v[80:83]
	v_add3_u32 v84, s12, v118, v138
	ds_write_b128 v84, v[104:107] offset:17408
	ds_write_b128 v84, v[72:75] offset:17424
	v_lshlrev_b32_e32 v72, 16, v76
	v_and_b32_e32 v73, 0xffff0000, v76
	v_pk_fma_f32 v[72:73], v[52:53], v[72:73], v[68:69]
	v_lshlrev_b32_e32 v74, 16, v88
	v_and_b32_e32 v75, 0xffff0000, v88
	v_pk_fma_f32 v[72:73], v[56:57], v[74:75], v[72:73]
	v_lshlrev_b32_e32 v74, 16, v92
	v_and_b32_e32 v75, 0xffff0000, v92
	v_pk_fma_f32 v[72:73], v[60:61], v[74:75], v[72:73]
	v_lshlrev_b32_e32 v74, 16, v100
	v_and_b32_e32 v75, 0xffff0000, v100
	v_pk_fma_f32 v[72:73], v[64:65], v[74:75], v[72:73]
	v_lshlrev_b32_e32 v74, 16, v77
	v_and_b32_e32 v75, 0xffff0000, v77
	v_pk_fma_f32 v[74:75], v[54:55], v[74:75], v[70:71]
	v_lshlrev_b32_e32 v76, 16, v89
	v_and_b32_e32 v77, 0xffff0000, v89
	v_pk_fma_f32 v[74:75], v[58:59], v[76:77], v[74:75]
	v_lshlrev_b32_e32 v76, 16, v93
	v_and_b32_e32 v77, 0xffff0000, v93
	v_pk_fma_f32 v[74:75], v[62:63], v[76:77], v[74:75]
	v_lshlrev_b32_e32 v76, 16, v101
	v_and_b32_e32 v77, 0xffff0000, v101
	v_pk_fma_f32 v[74:75], v[66:67], v[76:77], v[74:75]
	v_lshlrev_b32_e32 v76, 16, v78
	v_and_b32_e32 v77, 0xffff0000, v78
	v_pk_fma_f32 v[76:77], v[32:33], v[76:77], v[48:49]
	v_lshlrev_b32_e32 v80, 16, v90
	v_and_b32_e32 v81, 0xffff0000, v90
	v_pk_fma_f32 v[76:77], v[36:37], v[80:81], v[76:77]
	v_lshlrev_b32_e32 v80, 16, v94
	v_and_b32_e32 v81, 0xffff0000, v94
	v_pk_fma_f32 v[76:77], v[40:41], v[80:81], v[76:77]
	v_lshlrev_b32_e32 v80, 16, v102
	v_and_b32_e32 v81, 0xffff0000, v102
	v_lshlrev_b32_e32 v78, 16, v79
	v_and_b32_e32 v79, 0xffff0000, v79
	v_pk_fma_f32 v[76:77], v[44:45], v[80:81], v[76:77]
	v_pk_fma_f32 v[78:79], v[34:35], v[78:79], v[50:51]
	v_lshlrev_b32_e32 v80, 16, v91
	v_and_b32_e32 v81, 0xffff0000, v91
	v_pk_fma_f32 v[78:79], v[38:39], v[80:81], v[78:79]
	v_lshlrev_b32_e32 v80, 16, v95
	v_and_b32_e32 v81, 0xffff0000, v95
	v_pk_fma_f32 v[78:79], v[42:43], v[80:81], v[78:79]
	v_lshlrev_b32_e32 v80, 16, v103
	v_and_b32_e32 v81, 0xffff0000, v103
	v_pk_fma_f32 v[78:79], v[46:47], v[80:81], v[78:79]
	v_cvt_pk_bf16_f32 v80, v72, v73
	v_cvt_pk_bf16_f32 v81, v74, v75
	v_cvt_pk_bf16_f32 v82, v76, v77
	v_subrev_u32_e32 v112, 35, v126
	v_cvt_pk_bf16_f32 v83, v78, v79
	ds_write_b128 v85, v[80:83]
	ds_write_b128 v84, v[72:75] offset:34304
	ds_write_b128 v84, v[76:79] offset:34320
	v_cmp_lt_i32_e32 vcc, -1, v112
	v_mov_b32_e32 v84, 0
	v_mov_b32_e32 v72, 0
	v_mov_b32_e32 v73, 0
	v_mov_b32_e32 v74, 0
	v_mov_b32_e32 v75, 0
	s_waitcnt lgkmcnt(0)
	s_barrier
	s_and_saveexec_b64 s[10:11], vcc
	s_cbranch_execz .LBB0_601
	v_lshlrev_b64 v[72:73], 11, v[112:113]
	v_lshl_add_u64 v[72:73], v[122:123], 0, v[72:73]
	global_load_dwordx4 v[72:75], v[72:73], off
